# NSA selected-block list built in parallel with mbcnt/ballot positions instead of a 128-step serial scalar chain
# speedup vs baseline: 1.0113x; 1.0024x over previous
; #define LAS __attribute__((address_space(3)))
; DI void nsa_unit(const P& p, ldsp lds, int u, int l, int wv) {
;     ...
;         if (tid == 0) {
;             u64 ulo = 0, uhi = 0;
;             for (int k = 0; k < 8; ++k) { ulo |= *(LAS u64*)(lds + A_WUN + k * 16); uhi |= *(LAS u64*)(lds + A_WUN + k * 16 + 8); }
;             LAS int* list = (LAS int*)(lds + A_LIST); int cnt = 0;
;             for (int j = 63; j >= 0; --j) if ((uhi >> j) & 1ull) list[cnt++] = 64 + j;
;             for (int j = 63; j >= 0; --j) if ((ulo >> j) & 1ull) list[cnt++] = j;
;             list[128] = cnt;
;         }
;         __syncthreads();
;         c.ntiles = ((LAS int*)(lds + A_LIST))[128];
.LBB0_749:
	s_or_b64 exec, exec, s[2:3]
	v_cmp_eq_u32_e32 vcc, 0, v168
	s_waitcnt lgkmcnt(0)
	s_barrier
	s_and_saveexec_b64 s[2:3], vcc
	s_cbranch_execz .LBB0_881
	s_add_i32 s1, 0, 0x21e00
	v_mov_b32_e32 v0, s1
	ds_read_b128 v[66:69], v0
	v_readlane_b32 s1, v254, 25
	s_waitcnt lgkmcnt(0)
	v_readfirstlane_b32 s4, v66
	v_mov_b32_e32 v0, s1
	v_readfirstlane_b32 s5, v67
	v_readfirstlane_b32 s13, v69
	v_readfirstlane_b32 s12, v68
	ds_read_b128 v[66:69], v0
	v_readlane_b32 s1, v254, 26
	s_waitcnt lgkmcnt(0)
	v_readfirstlane_b32 s6, v66
	v_mov_b32_e32 v0, s1
	v_readfirstlane_b32 s7, v67
	v_readfirstlane_b32 s15, v69
	v_readfirstlane_b32 s14, v68
	ds_read_b128 v[66:69], v0
	v_readlane_b32 s1, v254, 27
	s_or_b64 s[14:15], s[14:15], s[12:13]
	s_waitcnt lgkmcnt(0)
	v_readfirstlane_b32 s12, v66
	v_mov_b32_e32 v0, s1
	v_readfirstlane_b32 s13, v67
	v_readfirstlane_b32 s21, v69
	v_readfirstlane_b32 s20, v68
	ds_read_b128 v[66:69], v0
	v_readlane_b32 s1, v254, 28
	s_or_b64 s[20:21], s[14:15], s[20:21]
	s_waitcnt lgkmcnt(0)
	v_readfirstlane_b32 s14, v66
	v_mov_b32_e32 v0, s1
	v_readfirstlane_b32 s15, v67
	v_readfirstlane_b32 s23, v69
	v_readfirstlane_b32 s22, v68
	ds_read_b128 v[66:69], v0
	v_readlane_b32 s1, v254, 29
	s_or_b64 s[20:21], s[20:21], s[22:23]
	s_waitcnt lgkmcnt(0)
	v_readfirstlane_b32 s44, v66
	v_mov_b32_e32 v0, s1
	v_readfirstlane_b32 s45, v67
	v_readfirstlane_b32 s23, v69
	v_readfirstlane_b32 s22, v68
	ds_read_b128 v[66:69], v0
	v_readlane_b32 s1, v254, 30
	s_or_b64 s[20:21], s[20:21], s[22:23]
	s_waitcnt lgkmcnt(0)
	v_readfirstlane_b32 s46, v66
	v_mov_b32_e32 v0, s1
	v_readfirstlane_b32 s47, v67
	v_readfirstlane_b32 s23, v69
	v_readfirstlane_b32 s22, v68
	ds_read_b128 v[66:69], v0
	v_readlane_b32 s1, v254, 31
	s_or_b64 s[20:21], s[20:21], s[22:23]
	s_waitcnt lgkmcnt(0)
	v_readfirstlane_b32 s48, v66
	v_mov_b32_e32 v0, s1
	v_readfirstlane_b32 s49, v67
	v_readfirstlane_b32 s23, v69
	v_readfirstlane_b32 s22, v68
	ds_read_b128 v[66:69], v0
	s_or_b64 s[20:21], s[20:21], s[22:23]
	s_mov_b32 s1, 0
	s_waitcnt lgkmcnt(0)
	v_readfirstlane_b32 s23, v69
	v_readfirstlane_b32 s22, v68
	s_or_b64 s[52:53], s[20:21], s[22:23]
	v_readfirstlane_b32 s50, v66
	v_readfirstlane_b32 s51, v67
	s_or_b64 s[4:5], s[4:5], s[6:7]
	s_or_b64 s[12:13], s[12:13], s[14:15]
	s_or_b64 s[44:45], s[44:45], s[46:47]
	s_or_b64 s[48:49], s[48:49], s[50:51]
	s_or_b64 s[4:5], s[4:5], s[12:13]
	s_or_b64 s[44:45], s[44:45], s[48:49]
	s_or_b64 s[4:5], s[4:5], s[44:45]
	s_bcnt1_i32_b64 s20, s[52:53]
	s_bcnt1_i32_b64 s21, s[4:5]
	s_add_i32 s21, s21, s20
	s_add_i32 s22, s20, -1
	s_add_i32 s23, s21, -1
	s_mov_b64 exec, -1
	v_mbcnt_lo_u32_b32 v66, s52, 0
	v_mbcnt_hi_u32_b32 v66, s53, v66
	v_mbcnt_lo_u32_b32 v67, s4, 0
	v_mbcnt_hi_u32_b32 v67, s5, v67
	v_mbcnt_lo_u32_b32 v0, -1, 0
	v_mbcnt_hi_u32_b32 v0, -1, v0
	v_sub_u32_e32 v66, s22, v66
	v_sub_u32_e32 v67, s23, v67
	v_lshlrev_b32_e32 v66, 2, v66
	v_lshlrev_b32_e32 v67, 2, v67
	v_add_u32_e32 v66, 0x21e80, v66
	v_add_u32_e32 v67, 0x21e80, v67
	v_add_u32_e32 v68, 64, v0
	s_mov_b64 exec, s[52:53]
	ds_write_b32 v66, v68
	s_mov_b64 exec, s[4:5]
	ds_write_b32 v67, v0
	s_mov_b64 exec, 1
	s_mov_b32 s1, s21
	s_mov_b32 s52, 0x800000
	s_mov_b32 s53, 0xff800000

; DI void zero_o(f32x16 (&o)[4]) {
; #pragma unroll
;     for (int db = 0; db < 4; ++db)
; #pragma unroll
;         for (int e = 0; e < 16; ++e) o[db][e] = 0.f;
; }
; DI void nsa_unit(const P& p, ldsp lds, int u, int l, int wv) {
;     ...
;     zero_o(o); c.m = NINF; c.l = 0.f; c.tile0 = 0; c.whi = 1 << 30;
;     c.kmat = heads + ((size_t)(28 + g) * M + b * T) * HD; c.vtm = VT + ((size_t)(8 + g) * (M / 64) + b * (T / 64)) * 8192; c.vpitch = 64;
;     attn_run<MD_SEL>(c, q, o, lds, tid, wv);
.LBB0_928:
	v_mov_b32_e32 v14, v1
	v_mov_b32_e32 v15, v1
	v_mov_b32_e32 v0, v1
	v_mov_b32_e32 v2, v1
	v_mov_b32_e32 v3, v1
	v_mov_b32_e32 v4, v1
	v_mov_b32_e32 v5, v1
	v_mov_b32_e32 v6, v1
	v_mov_b32_e32 v7, v1
	v_mov_b32_e32 v8, v1
	v_mov_b32_e32 v9, v1
	v_mov_b32_e32 v10, v1
	v_mov_b32_e32 v11, v1
	v_mov_b32_e32 v12, v1
	v_mov_b32_e32 v13, v1
	v_mov_b64_e32 v[32:33], v[14:15]
	v_mov_b64_e32 v[48:49], v[14:15]
	v_mov_b64_e32 v[64:65], v[14:15]
	v_mov_b64_e32 v[80:81], v[14:15]
	v_mov_b32_e32 v210, 0
	v_mov_b64_e32 v[30:31], v[12:13]
	v_mov_b64_e32 v[28:29], v[10:11]
	v_mov_b64_e32 v[26:27], v[8:9]
	v_mov_b64_e32 v[24:25], v[6:7]
	v_mov_b64_e32 v[22:23], v[4:5]
	v_mov_b64_e32 v[20:21], v[2:3]
	v_mov_b64_e32 v[18:19], v[0:1]
	v_mov_b64_e32 v[46:47], v[12:13]
	v_mov_b64_e32 v[44:45], v[10:11]
	v_mov_b64_e32 v[42:43], v[8:9]
	v_mov_b64_e32 v[40:41], v[6:7]
	v_mov_b64_e32 v[38:39], v[4:5]
	v_mov_b64_e32 v[36:37], v[2:3]
	v_mov_b64_e32 v[34:35], v[0:1]
	v_mov_b64_e32 v[62:63], v[12:13]
	v_mov_b64_e32 v[60:61], v[10:11]
	v_mov_b64_e32 v[58:59], v[8:9]
	v_mov_b64_e32 v[56:57], v[6:7]
	v_mov_b64_e32 v[54:55], v[4:5]
	v_mov_b64_e32 v[52:53], v[2:3]
	v_mov_b64_e32 v[50:51], v[0:1]
	v_mov_b64_e32 v[78:79], v[12:13]
	v_mov_b64_e32 v[76:77], v[10:11]
	v_mov_b64_e32 v[74:75], v[8:9]
	v_mov_b64_e32 v[72:73], v[6:7]
	v_mov_b64_e32 v[70:71], v[4:5]
	v_mov_b64_e32 v[68:69], v[2:3]
	v_mov_b64_e32 v[66:67], v[0:1]
	s_branch .LBB0_1056
.LBB0_1055:
	v_readlane_b32 s24, v255, 19
